# D-up GEMM schedule after the rebalancing made XCD-consistent again: tile index keeps L % 8 == blockIdx % 8 (stride 8 instead of consecutive tiles), so each XCD works on one contiguous tile region whos
# speedup vs baseline: 1.0045x; 1.0045x over previous
;     DI bool next(int i, Unit& u) const {
;         const long L = (long)i * G + c; if (L >= nwg) return false;
;         int wgid = (int)L; { const int q = nwg / NXCD, r = nwg % NXCD, xcd = wgid % NXCD, off = wgid / NXCD; wgid = (xcd < r ? xcd * (q + 1) : r * (q + 1) + (xcd - r) * q) + off; }
;         const int nig = WGM * nN, gid = wgid / nig, fm = gid * WGM, gsz = (nM - fm) < WGM ? (nM - fm) : WGM;
;         u.pm = fm + ((wgid % nig) % gsz); u.pn = (wgid % nig) / gsz;
;         u.aoff = (size_t)u.pm * 256 * lda * 2; u.boff = (size_t)u.pn * 256 * K * 2;
;         if (MODE == 1 && u.pn >= 12) u.aoff += 1024;
;         if (MODE == 2) u.aoff += (size_t)(u.pn >> 1) * 512;
;         return true;
; template <class Epi, class SchedT>
; DI void gemm_phase(LAS unsigned char* lds, const bf16_t* Ap, const bf16_t* Btp, const int K, const int lda, const SchedT& S, const Epi& E) {
;     const int tid = otid(), wid = __builtin_amdgcn_readfirstlane(tid >> 6), lane = tid & 63, wr = wid >> 2, wc = wid & 3, fr = lane & 15, fq = lane >> 4;
;     const int nt = K / BK;
;     unsigned voffA[2], voffB[2];
; #pragma unroll
;     for (int i = 0; i < 2; ++i) { int R, C; stage_rc(tid * 16 + i * 8192, R, C); const int Rb = (R & ~31) + perm32(R & 31);
;         voffA[i] = (unsigned)(R * lda + C) * 2u; voffB[i] = (unsigned)(Rb * K + C) * 2u; }
;     const size_t kstep = (size_t)(BK * 2);
;     const size_t hstepA = (size_t)HALF * lda * 2, hstepB = (size_t)HALF * K * 2;
;     const unsigned ldsw = (unsigned)wid * 1024u;
;     const int aoff = lds_byte(wr * 64 + fr, fq * 8), boff = lds_byte(wc * 32 + fr, fq * 8);
;     ...
;     Unit cur, nxt; int ui = 0;
;     if (!S.next(0, cur)) return;
;     float pre[8]; E.prefetch(cur, wr, fr, pre);
;     f32x4 acc[2][2][4][2];
; #pragma unroll
;     for (int a = 0; a < 2; ++a)
; #pragma unroll
;         for (int b = 0; b < 2; ++b)
; #pragma unroll
;             for (int m = 0; m < 4; ++m)
; #pragma unroll
;                 for (int n = 0; n < 2; ++n) acc[a][b][m][n] = (f32x4){0.f, 0.f, 0.f, 0.f};
;     bf16x8 At[4][2], B0[2][2], B1[2][2];
;     const char* cA = (const char*)Ap + cur.aoff; const char* cB = (const char*)Btp + cur.boff;
;     PG8_STAGE(PG8_SB(0, 0), cB, voffB); PG8_STAGE(PG8_SA(0, 0), cA, voffA); PG8_STAGE(PG8_SB(0, 1), cB + hstepB, voffB); PG8_STAGE(PG8_SA(0, 1), cA + hstepA, voffA);
;     if (wr == 1) PG8_BAR;
.Ldi_1306:
	s_waitcnt lgkmcnt(0)
	s_barrier
	s_and_b32 s95, s2, 7
	s_lshr_b32 s94, s2, 3
	s_lshl_b32 s94, s94, 5
	s_addk_i32 s94, 0x600
	s_add_i32 s94, s94, s95
	s_sub_i32 s92, s2, 64
	s_lshr_b32 s92, s92, 3
	s_lshl_b32 s92, s92, 6
	s_add_i32 s92, s92, s95
	s_cmp_lt_u32 s2, 64
	s_cselect_b32 s94, s94, s92
	s_cselect_b32 s95, 24, 56
	s_add_i32 s92, s94, s95
	s_add_i32 s95, s92, 1
	s_load_dwordx2 s[8:9], s[0:1], 0xf0
	s_movk_i32 s6, 0x200
	v_mov_b32_e32 v14, v181
	s_cmpk_gt_i32 s94, 0x6ff
	v_readfirstlane_b32 s3, v14
	s_cbranch_scc1 .LBB0_1373
	v_lshlrev_b32_e32 v0, 4, v14
	v_add_u32_e32 v1, 0x2000, v0
	v_ashrrev_i32_e32 v2, 31, v1
	v_lshrrev_b32_e32 v2, 22, v2
	v_add_u32_e32 v2, v1, v2
	v_ashrrev_i32_e32 v12, 10, v2
	v_mul_i32_i24_e32 v2, 0x400, v12
	v_sub_u32_e32 v1, v1, v2
	v_lshrrev_b32_e32 v2, 4, v1
	v_bitop3_b32 v1, v2, v1, 32 bitop3:0x6c
	v_ashrrev_i32_e32 v2, 31, v1
	v_lshrrev_b32_e32 v2, 26, v2
	v_add_u32_e32 v2, v1, v2
	v_lshlrev_b32_e32 v3, 3, v12
	v_ashrrev_i32_e32 v15, 6, v2
	v_and_b32_e32 v3, -16, v3
	v_add_u32_e32 v3, v15, v3
	v_and_b32_e32 v4, 3, v15
	s_mov_b32 s12, 0x7fffffe0
	v_lshrrev_b32_e32 v5, 2, v3
	v_lshlrev_b32_e32 v6, 1, v3
	v_and_b32_e32 v2, 0xc0, v2
	v_and_or_b32 v4, v3, s12, v4
	v_and_b32_e32 v5, 4, v5
	v_and_b32_e32 v6, 24, v6
	v_sub_u32_e32 v1, v1, v2
	v_mov_b32_e32 v2, 1
	v_or3_b32 v4, v4, v5, v6
	v_lshlrev_b32_e32 v5, 5, v12
	v_ashrrev_i16_sdwa v1, v2, sext(v1) dst_sel:DWORD dst_unused:UNUSED_PAD src0_sel:DWORD src1_sel:BYTE_0
	v_and_b32_e32 v16, 32, v5
	v_bfe_i32 v17, v1, 0, 16
	s_movk_i32 s27, 0x440
	v_mul_lo_u32 v4, v4, s6
	v_add_u32_e32 v1, v16, v17
	v_mul_lo_u32 v3, v3, s27
	v_add_lshl_u32 v128, v4, v1, 1
	v_add_lshl_u32 v130, v1, v3, 1
	v_bfe_i32 v1, v14, 27, 1
	v_lshrrev_b32_e32 v1, 22, v1
	v_add_u32_e32 v1, v0, v1
	v_and_b32_e32 v1, 0xfffffc00, v1
	v_sub_u32_e32 v0, v0, v1
	v_lshrrev_b32_e32 v1, 4, v0
	v_bitop3_b32 v1, v1, v0, 32 bitop3:0x6c
	v_ashrrev_i32_e32 v0, 31, v0
	v_lshrrev_b32_e32 v0, 26, v0
	v_add_u32_e32 v0, v1, v0
	v_ashrrev_i32_e32 v18, 6, v0
	v_ashrrev_i32_e32 v0, 31, v14
	v_lshrrev_b32_e32 v0, 26, v0
	v_add_u32_e32 v0, v14, v0
	s_waitcnt lgkmcnt(0)
	s_add_u32 s44, s8, 0x1ff40000
	v_ashrrev_i32_e32 v19, 6, v0
	s_addc_u32 s45, s9, 0
	v_lshlrev_b32_e32 v0, 3, v19
	s_add_u32 s46, s8, 0x7000000
	v_and_b32_e32 v0, -16, v0
	s_addc_u32 s47, s9, 0
	v_add_u32_e32 v0, v18, v0
	v_and_b32_e32 v3, 3, v18
	s_ashr_i32 s49, s94, 31
	v_and_or_b32 v3, v0, s12, v3
	s_lshr_b32 s12, s49, 29
	s_add_i32 s12, s94, s12
	s_ashr_i32 s25, s3, 6
	s_ashr_i32 s26, s3, 8
	s_ashr_i32 s7, s6, 31
	s_ashr_i32 s13, s12, 3
	s_and_b32 s12, s12, -8
	s_lshl_b64 s[10:11], s[6:7], 8
	s_lshl_b32 s48, s25, 10
	s_lshl_b32 s28, s26, 6
	s_sub_i32 s12, s94, s12
	s_cmp_lt_i32 s12, 0
	s_movk_i32 s50, 0xe1
	s_cselect_b32 s14, s50, 0xe0
	s_mul_i32 s12, s14, s12
	s_add_i32 s12, s12, s13
	s_mul_hi_i32 s13, s12, 0x92492493
	s_add_i32 s13, s13, s12
	s_lshr_b32 s14, s13, 31
	s_ashr_i32 s13, s13, 7
	s_add_i32 s13, s13, s14
	s_lshl_b32 s14, s13, 3
	s_mulk_i32 s13, 0xe0
	s_sub_i32 s16, s12, s13
	s_sext_i32_i16 s12, s16
	s_bfe_u32 s12, s12, 0x3001c
	s_add_i32 s12, s16, s12
	s_sext_i32_i16 s17, s12
	s_and_b32 s12, s12, 0xfff8
	s_sub_i32 s12, s16, s12
	s_lshr_b32 s24, s17, 3
	s_sext_i32_i16 s12, s12
	s_add_i32 s70, s14, s12
	s_bfe_i64 s[14:15], s[24:25], 0x100000
	s_lshl_b64 s[12:13], s[6:7], 9
	s_ashr_i32 s17, s17, 3
	s_mul_hi_u32 s14, s12, s17
	s_mul_i32 s15, s12, s15
	v_lshrrev_b32_e32 v4, 2, v0
	v_lshlrev_b32_e32 v5, 1, v0
	s_add_i32 s31, s14, s15
	s_lshr_b64 s[14:15], s[6:7], 23
	v_and_b32_e32 v4, 4, v4
	v_and_b32_e32 v5, 24, v5
	s_mul_i32 s29, s70, 0x88000
	s_mul_i32 s14, s14, s17
	v_or3_b32 v3, v3, v4, v5
	v_lshlrev_b32_e32 v4, 5, v19
	s_or_b32 s30, s29, 0x400
	s_add_i32 s31, s31, s14
	v_and_b32_e32 v20, 32, v4
	v_mul_i32_i24_e32 v4, 64, v18
	s_cmpk_gt_i32 s16, 0x5f
	v_sub_u32_e32 v1, v1, v4
	s_cselect_b32 s14, 0x10000, 0
	v_ashrrev_i16_sdwa v1, v2, sext(v1) dst_sel:DWORD dst_unused:UNUSED_PAD src0_sel:DWORD src1_sel:BYTE_0
	s_cselect_b32 s29, s30, s29
	s_add_u32 s14, s44, s14
	v_bfe_i32 v21, v1, 0, 16
	s_addc_u32 s15, s45, 0
	s_lshl_b32 s30, s70, 8
	v_and_b32_e32 v13, 15, v14
	v_add_u32_e32 v1, v20, v21
	v_mul_lo_u32 v0, v0, s27
	s_mul_i32 s17, s12, s17
	s_add_i32 s30, s28, s30
	v_mul_lo_u32 v3, v3, s6
	v_add_lshl_u32 v134, v1, v0, 1
	v_or_b32_e32 v0, s30, v13
	s_add_u32 s38, s46, s17
	v_add_lshl_u32 v132, v3, v1, 1
	v_ashrrev_i32_e32 v1, 31, v0
	s_addc_u32 s39, s47, s31
	s_add_i32 s51, s48, 0
	v_lshl_add_u64 v[0:1], v[0:1], 2, s[14:15]
	s_add_i32 m0, s51, 0x10000
	flat_load_dword v146, v[0:1]
	flat_load_dword v161, v[0:1] offset:64
	flat_load_dword v160, v[0:1] offset:128
	flat_load_dword v159, v[0:1] offset:192
	flat_load_dword v158, v[0:1] offset:512
	flat_load_dword v157, v[0:1] offset:576
	flat_load_dword v150, v[0:1] offset:640
	flat_load_dword v148, v[0:1] offset:704
	s_mul_hi_i32 s16, s70, 0x88000
	global_load_lds_dwordx4 v132, s[38:39]
	s_add_i32 m0, s51, 0x12000
	s_add_u32 s36, s8, s29
	global_load_lds_dwordx4 v128, s[38:39]
	s_addc_u32 s37, s9, s16
	s_mov_b32 m0, s51
	s_add_i32 s52, s51, 0x2000
	global_load_lds_dwordx4 v134, s[36:37]
	s_mov_b32 m0, s52
	s_add_u32 s14, s38, s10
	global_load_lds_dwordx4 v130, s[36:37]
	s_addc_u32 s15, s39, s11
	s_add_i32 m0, s51, 0x14000
	v_mov_b32_e32 v133, 0
	global_load_lds_dwordx4 v132, s[14:15]
	s_add_i32 m0, s51, 0x16000
	s_add_u32 s16, s36, 0x44000
	s_addc_u32 s17, s37, 0
	s_add_i32 s53, s51, 0x4000
	global_load_lds_dwordx4 v128, s[14:15]
	s_mov_b32 m0, s53
	s_add_i32 s54, s51, 0x6000
	global_load_lds_dwordx4 v134, s[16:17]
	s_mov_b32 m0, s54
	v_mov_b32_e32 v129, v133
	global_load_lds_dwordx4 v130, s[16:17]
	v_mov_b32_e32 v135, v133
	v_mov_b32_e32 v131, v133
	s_mov_b32 s55, 0
	v_lshl_add_u64 v[10:11], s[38:39], 0, v[132:133]
	v_lshl_add_u64 v[8:9], s[38:39], 0, v[128:129]
	v_lshl_add_u64 v[6:7], s[36:37], 0, v[134:135]
	v_lshl_add_u64 v[4:5], s[36:37], 0, v[130:131]
	v_lshl_add_u64 v[2:3], s[14:15], 0, v[132:133]
	s_cmp_lg_u32 s26, 1
	v_lshl_add_u64 v[0:1], s[14:15], 0, v[128:129]
	s_cbranch_scc1 .LBB0_1361
	s_barrier
; #define PG8_STAGE(bufoff, gbase, voff) do { _Pragma("unroll") for (int _i = 0; _i < 2; ++_i) \
;         __builtin_amdgcn_global_load_lds((const unsigned*)((const char*)(gbase) + (voff)[_i]), (LAS unsigned*)(lds + (bufoff) + ldsw + _i * 8192), 16, 0, 0); } while (0)
; #define PG8_WAIT_V(n) asm volatile("s_waitcnt vmcnt(" #n ")" ::: "memory")
; #define PG8_BAR __builtin_amdgcn_s_barrier()
; template <class Epi, class SchedT>
; DI void gemm_phase(LAS unsigned char* lds, const bf16_t* Ap, const bf16_t* Btp, const int K, const int lda, const SchedT& S, const Epi& E) {
;     ...
;     if (wr == 1) PG8_BAR;
;     PG8_WAIT_V(4); PG8_BAR;
;     PG8_STAGE(PG8_SB(1, 0), cB + kstep, voffB); PG8_STAGE(PG8_SA(1, 0), cA + kstep, voffA); PG8_STAGE(PG8_SB(1, 1), cB + hstepB + kstep, voffB);
;     PG8_WAIT_V(6); PG8_BAR;
;     for (;;) {
;         const bool has_next = S.next(ui + 1, nxt);
;         const char* nA = has_next ? (const char*)Ap + nxt.aoff : cA; const char* nB = has_next ? (const char*)Btp + nxt.boff : cB;
.LBB0_1361:
	s_add_u32 s14, s8, 0xbf00000
	s_mov_b64 s[16:17], 0x80
	s_addc_u32 s15, s9, 0
	s_add_i32 m0, s51, 0x18000
	v_lshl_add_u64 v[10:11], v[10:11], 0, s[16:17]
	s_waitcnt vmcnt(4)
	s_barrier
	global_load_lds_dwordx4 v[10:11], off
	v_lshl_add_u64 v[8:9], v[8:9], 0, s[16:17]
	s_add_i32 m0, s51, 0x1a000
	s_add_i32 s56, s51, 0x8000
	global_load_lds_dwordx4 v[8:9], off
	v_lshl_add_u64 v[6:7], v[6:7], 0, s[16:17]
	s_mov_b32 m0, s56
	s_add_i32 s57, s51, 0xa000
	global_load_lds_dwordx4 v[6:7], off
	v_lshl_add_u64 v[4:5], v[4:5], 0, s[16:17]
	s_mov_b32 m0, s57
	v_lshl_add_u64 v[2:3], v[2:3], 0, s[16:17]
	global_load_lds_dwordx4 v[4:5], off
	s_add_i32 m0, s51, 0x1c000
	v_lshl_add_u64 v[0:1], v[0:1], 0, s[16:17]
	global_load_lds_dwordx4 v[2:3], off
	s_add_i32 m0, s51, 0x1e000
	s_lshr_b32 s7, s7, 26
	global_load_lds_dwordx4 v[0:1], off
	v_lshrrev_b32_e32 v0, 1, v14
	s_add_i32 s7, s6, s7
	v_or_b32_e32 v149, s28, v13
	v_and_b32_e32 v0, 24, v0
	s_ashr_i32 s58, s7, 6
	v_lshlrev_b32_e32 v1, 6, v149
	v_lshlrev_b32_e32 v2, 1, v0
	s_movk_i32 s7, 0x3c0
	v_lshlrev_b32_e32 v3, 2, v149
	v_and_or_b32 v1, v1, s7, v2
	s_lshl_b32 s7, s26, 13
	v_and_b32_e32 v3, 32, v3
	v_bitop3_b32 v3, v1, s7, v3 bitop3:0xde
	s_lshl_b32 s7, s25, 5
	s_and_b32 s7, s7, 0x60
	v_lshl_or_b32 v1, v13, 6, v2
	v_lshlrev_b32_e32 v2, 2, v13
	s_sext_i32_i16 s71, s24
	s_lshl_b32 s24, s7, 7
	v_and_b32_e32 v2, 32, v2
	v_bitop3_b32 v151, v1, s24, v2 bitop3:0xde
	v_or_b32_e32 v152, s7, v0
	v_lshrrev_b32_e32 v1, 1, v12
	v_mul_lo_u32 v0, v15, s27
	s_movk_i32 s26, 0x4400
	s_cmp_gt_i32 s6, 63
	v_mad_u64_u32 v[0:1], s[6:7], v1, s26, v[0:1]
	v_or_b32_e32 v0, v0, v16
	v_add_lshl_u32 v0, v0, v17, 1
	v_mov_b32_e32 v1, v133
	s_mov_b64 s[6:7], 0x44080
	s_waitcnt vmcnt(0)
	v_lshl_add_u64 v[136:137], v[0:1], 0, s[6:7]
	v_lshrrev_b32_e32 v1, 1, v19
	v_mul_lo_u32 v0, v18, s27
	v_mad_u64_u32 v[0:1], s[26:27], v1, s26, v[0:1]
	s_waitcnt vmcnt(6)
	v_or_b32_e32 v0, v0, v20
	s_cselect_b64 s[24:25], -1, 0
	v_add_lshl_u32 v0, v0, v21, 1
	v_mov_b32_e32 v1, v133
	s_add_i32 s64, 0, 0x10000
	s_add_i32 s65, 0, 0x14000
	s_add_i32 s59, s58, -2
	s_mov_b32 s60, 0
	s_mov_b32 s61, 8
	v_lshl_add_u64 v[138:139], v[0:1], 0, s[6:7]
	v_mov_b32_e32 v140, s95
	v_mov_b32_e32 v141, 0
	v_mov_b32_e32 v142, s92
	v_mov_b32_e32 v143, 0
	v_add_u32_e32 v153, s64, v151
	v_add_u32_e32 v154, 0, v3
	v_add_u32_e32 v155, s65, v151
	s_movk_i32 s66, 0x3800
	v_mov_b32_e32 v156, 0x358637bd
	s_mov_b32 s67, 0x800000
	s_barrier
	s_branch .LBB0_1363
